# scan loader: each register set refilled with record m+3 right after its LDS write (prefetch distance ~3 chunks), waits 35..22
# speedup vs baseline: 1.0324x; 1.0324x over previous
; #define LAS __attribute__((address_space(3)))
; #define LDSBAR() do { asm volatile("s_waitcnt lgkmcnt(0)" ::: "memory"); __builtin_amdgcn_s_barrier(); asm volatile("" ::: "memory"); } while (0)
; DI void gdn_scan(const Args& a, int l, int bh, LAS unsigned char* lds, const int tidx, const bool nostore) {
;     ...
;         const int pidx = tid - 256, sub = pidx & 15;
;         u32x4 pfa[14], pfb[14];
; #pragma unroll
;         for (int i = 0; i < 14; ++i) pfb[i] = *(const u32x4*)(rec + (size_t)(pidx + 256 * i) * 16);
; #pragma unroll
;         for (int i = 0; i < 14; ++i) pfa[i] = *(const u32x4*)(rec + REC_BYTES + (size_t)(pidx + 256 * i) * 16);
; #pragma unroll
;         for (int i = 0; i < 14; ++i) *(LAS u32x4*)(lds + (pidx + 256 * i) * 16) = pfb[i];
;         LDSBAR();
;         bf16_t* obase = proj + ((size_t)b * SEQ + (pidx >> 4)) * NPROJ + C_GV + h * 128 + sub * 8;
;     ...
;         for (int n2 = 0; n2 < 64; n2 += 2) {
;             LOADER_ITER(n2, pfa, pfb);
;             LOADER_ITER(n2 + 1, pfb, pfa);
;         }
;         LOADER_ITER(64, pfa, pfb);
.LBB0_363:
	s_add_u32 s6, s6, 0x2a000
	s_addc_u32 s7, s7, 0
	v_lshl_add_u64 v[56:57], s[6:7], 0, v[114:115]
	v_lshl_add_u64 v[60:61], s[6:7], 0, v[116:117]
	v_lshl_add_u64 v[64:65], s[6:7], 0, v[118:119]
	v_lshl_add_u64 v[68:69], s[6:7], 0, v[120:121]
	v_lshl_add_u64 v[72:73], s[6:7], 0, v[122:123]
	v_lshl_add_u64 v[76:77], s[6:7], 0, v[124:125]
	v_lshl_add_u64 v[80:81], s[6:7], 0, v[126:127]
	v_lshl_add_u64 v[84:85], s[6:7], 0, v[128:129]
	v_lshl_add_u64 v[88:89], s[6:7], 0, v[130:131]
	v_lshl_add_u64 v[92:93], s[6:7], 0, v[132:133]
	v_lshl_add_u64 v[96:97], s[6:7], 0, v[134:135]
	v_lshl_add_u64 v[100:101], s[6:7], 0, v[136:137]
	v_lshl_add_u64 v[104:105], s[6:7], 0, v[138:139]
	v_lshl_add_u64 v[108:109], s[6:7], 0, v[140:141]
	global_load_dwordx4 v[56:59], v[56:57], off
	s_nop 0
	global_load_dwordx4 v[60:63], v[60:61], off
	s_nop 0
	global_load_dwordx4 v[64:67], v[64:65], off
	s_nop 0
	global_load_dwordx4 v[68:71], v[68:69], off
	s_nop 0
	global_load_dwordx4 v[72:75], v[72:73], off
	s_nop 0
	global_load_dwordx4 v[76:79], v[76:77], off
	s_nop 0
	global_load_dwordx4 v[80:83], v[80:81], off
	s_nop 0
	global_load_dwordx4 v[84:87], v[84:85], off
	s_nop 0
	global_load_dwordx4 v[88:91], v[88:89], off
	s_nop 0
	global_load_dwordx4 v[92:95], v[92:93], off
	s_nop 0
	global_load_dwordx4 v[96:99], v[96:97], off
	s_nop 0
	global_load_dwordx4 v[100:103], v[100:101], off
	s_nop 0
	global_load_dwordx4 v[104:107], v[104:105], off
	s_nop 0
	global_load_dwordx4 v[108:111], v[108:109], off
	global_load_dword v192, v[112:113], off
	global_load_dword v192, v[112:113], off
	global_load_dword v192, v[112:113], off
	global_load_dword v192, v[112:113], off
	s_add_u32 s6, s42, s13
	v_readlane_b32 s5, v254, 29
	s_addc_u32 s7, s43, s12
	v_lshl_add_u64 v[114:115], s[6:7], 0, v[114:115]
	v_lshl_add_u32 v144, v143, 1, s5
	v_lshl_add_u64 v[116:117], s[6:7], 0, v[116:117]
	v_lshl_add_u64 v[118:119], s[6:7], 0, v[118:119]
	v_lshl_add_u64 v[120:121], s[6:7], 0, v[120:121]
	v_lshl_add_u64 v[122:123], s[6:7], 0, v[122:123]
	v_lshl_add_u64 v[124:125], s[6:7], 0, v[124:125]
	v_lshl_add_u64 v[126:127], s[6:7], 0, v[126:127]
	v_lshl_add_u64 v[128:129], s[6:7], 0, v[128:129]
	v_lshl_add_u64 v[130:131], s[6:7], 0, v[130:131]
	v_lshl_add_u64 v[132:133], s[6:7], 0, v[132:133]
	v_lshl_add_u64 v[134:135], s[6:7], 0, v[134:135]
	v_lshl_add_u64 v[136:137], s[6:7], 0, v[136:137]
	v_lshl_add_u64 v[138:139], s[6:7], 0, v[138:139]
	v_lshl_add_u64 v[140:141], s[6:7], 0, v[140:141]
	v_mad_i64_i32 v[142:143], s[6:7], v142, s47, 0
	v_mad_i64_i32 v[142:143], s[4:5], s4, v243, v[142:143]
	s_waitcnt vmcnt(27)
	ds_write_b128 v174, v[0:3]
	s_waitcnt vmcnt(26)
	ds_write_b128 v174, v[4:7] offset:4096
	s_waitcnt vmcnt(25)
	ds_write_b128 v174, v[8:11] offset:8192
	s_waitcnt vmcnt(24)
	ds_write_b128 v174, v[12:15] offset:12288
	s_waitcnt vmcnt(23)
	ds_write_b128 v174, v[16:19] offset:16384
	s_waitcnt vmcnt(22)
	ds_write_b128 v174, v[20:23] offset:20480
	s_waitcnt vmcnt(21)
	ds_write_b128 v174, v[24:27] offset:24576
	s_waitcnt vmcnt(20)
	ds_write_b128 v174, v[28:31] offset:28672
	s_waitcnt vmcnt(19)
	ds_write_b128 v174, v[32:35] offset:32768
	s_waitcnt vmcnt(18)
	ds_write_b128 v174, v[36:39] offset:36864
	s_waitcnt vmcnt(17)
	ds_write_b128 v174, v[40:43] offset:40960
	s_waitcnt vmcnt(16)
	ds_write_b128 v174, v[44:47] offset:45056
	s_waitcnt vmcnt(15)
	ds_write_b128 v174, v[48:51] offset:49152
	s_waitcnt vmcnt(14)
	ds_write_b128 v174, v[52:55] offset:53248
	s_waitcnt lgkmcnt(0)
	v_add_u32_e32 v178, v144, v176
	v_lshl_add_u64 v[172:173], v[114:115], 0, s[94:95]
	v_lshl_add_u64 v[170:171], v[116:117], 0, s[94:95]
	v_lshl_add_u64 v[168:169], v[118:119], 0, s[94:95]
	v_lshl_add_u64 v[166:167], v[120:121], 0, s[94:95]
	v_lshl_add_u64 v[164:165], v[122:123], 0, s[94:95]
	v_lshl_add_u64 v[160:161], v[124:125], 0, s[94:95]
	v_lshl_add_u64 v[158:159], v[126:127], 0, s[94:95]
	v_lshl_add_u64 v[156:157], v[128:129], 0, s[94:95]
	v_lshl_add_u64 v[154:155], v[130:131], 0, s[94:95]
	v_lshl_add_u64 v[152:153], v[132:133], 0, s[94:95]
	v_lshl_add_u64 v[150:151], v[134:135], 0, s[94:95]
	v_lshl_add_u64 v[148:149], v[136:137], 0, s[94:95]
	v_lshl_add_u64 v[146:147], v[138:139], 0, s[94:95]
	v_lshl_add_u64 v[144:145], v[140:141], 0, s[94:95]
	v_add_co_u32_e32 v0, vcc, 0x15538000, v172
	s_nop 1
	v_addc_co_u32_e32 v1, vcc, 0, v173, vcc
	v_add_co_u32_e32 v4, vcc, 0x15538000, v170
	global_load_dwordx4 v[0:3], v[0:1], off
	s_nop 0
	v_addc_co_u32_e32 v5, vcc, 0, v171, vcc
	v_add_co_u32_e32 v8, vcc, 0x15538000, v168
	global_load_dwordx4 v[4:7], v[4:5], off
	s_nop 0
	v_addc_co_u32_e32 v9, vcc, 0, v169, vcc
	v_add_co_u32_e32 v12, vcc, 0x15538000, v166
	global_load_dwordx4 v[8:11], v[8:9], off
	s_nop 0
	v_addc_co_u32_e32 v13, vcc, 0, v167, vcc
	v_add_co_u32_e32 v16, vcc, 0x15538000, v164
	global_load_dwordx4 v[12:15], v[12:13], off
	s_nop 0
	v_addc_co_u32_e32 v17, vcc, 0, v165, vcc
	v_add_co_u32_e32 v20, vcc, 0x15538000, v160
	global_load_dwordx4 v[16:19], v[16:17], off
	s_nop 0
	v_addc_co_u32_e32 v21, vcc, 0, v161, vcc
	v_add_co_u32_e32 v24, vcc, 0x15538000, v158
	global_load_dwordx4 v[20:23], v[20:21], off
	s_nop 0
	v_addc_co_u32_e32 v25, vcc, 0, v159, vcc
	v_add_co_u32_e32 v28, vcc, 0x15538000, v156
	global_load_dwordx4 v[24:27], v[24:25], off
	s_nop 0
	v_addc_co_u32_e32 v29, vcc, 0, v157, vcc
	v_add_co_u32_e32 v32, vcc, 0x15538000, v154
	global_load_dwordx4 v[28:31], v[28:29], off
	s_nop 0
	v_addc_co_u32_e32 v33, vcc, 0, v155, vcc
	v_add_co_u32_e32 v36, vcc, 0x15538000, v152
	global_load_dwordx4 v[32:35], v[32:33], off
	s_nop 0
	v_addc_co_u32_e32 v37, vcc, 0, v153, vcc
	v_add_co_u32_e32 v40, vcc, 0x15538000, v150
	global_load_dwordx4 v[36:39], v[36:37], off
	s_nop 0
	v_addc_co_u32_e32 v41, vcc, 0, v151, vcc
	v_add_co_u32_e32 v44, vcc, 0x15538000, v148
	global_load_dwordx4 v[40:43], v[40:41], off
	s_nop 0
	v_addc_co_u32_e32 v45, vcc, 0, v149, vcc
	v_add_co_u32_e32 v48, vcc, 0x15538000, v146
	global_load_dwordx4 v[44:47], v[44:45], off
	s_nop 0
	v_addc_co_u32_e32 v49, vcc, 0, v147, vcc
	v_add_co_u32_e32 v52, vcc, 0x15538000, v144
	global_load_dwordx4 v[48:51], v[48:49], off
	s_nop 0
	v_addc_co_u32_e32 v53, vcc, 0, v145, vcc
	global_load_dwordx4 v[52:55], v[52:53], off
	s_and_b64 vcc, exec, s[0:1]
	s_cbranch_vccnz .Lldr_p1_st_done
	ds_read_b128 v[180:183], v177
	v_add_co_u32_e32 v184, vcc, 0x36000, v112
	s_waitcnt lgkmcnt(0)
	global_store_dwordx4 v[112:113], v[180:183], off
	ds_read_b128 v[180:183], v177 offset:4352
	v_addc_co_u32_e32 v185, vcc, 0, v113, vcc
	s_waitcnt lgkmcnt(0)
	global_store_dwordx4 v[184:185], v[180:183], off
	ds_read_b128 v[180:183], v177 offset:8704
	v_add_co_u32_e32 v184, vcc, 0x6c000, v112
	s_nop 1
	v_addc_co_u32_e32 v185, vcc, 0, v113, vcc
	s_waitcnt lgkmcnt(0)
	global_store_dwordx4 v[184:185], v[180:183], off
	ds_read_b128 v[180:183], v177 offset:13056
	v_add_co_u32_e32 v184, vcc, 0xa2000, v112
	s_nop 1
	v_addc_co_u32_e32 v185, vcc, 0, v113, vcc
	s_waitcnt lgkmcnt(0)
	global_store_dwordx4 v[184:185], v[180:183], off
; DI void gdn_scan(const Args& a, int l, int bh, LAS unsigned char* lds, const int tidx, const bool nostore) {
;     ...
;         bf16_t* obase = proj + ((size_t)b * SEQ + (pidx >> 4)) * NPROJ + C_GV + h * 128 + sub * 8;
;     ...
;         for (int n2 = 0; n2 < 64; n2 += 2) {
.Lldr_p1_st_done:
	s_lshl_b64 s[4:5], s[8:9], 1
	s_waitcnt lgkmcnt(0)
	s_barrier
	v_and_b32_e32 v145, 15, v220
	s_add_u32 s4, s42, s4
	v_lshl_or_b32 v142, v145, 4, v142
	s_addc_u32 s5, s43, s5
	v_lshl_add_u64 v[142:143], s[4:5], 0, v[142:143]
	s_mov_b32 s6, 2
	s_branch .LBB0_365

; DI void gdn_scan(const Args& a, int l, int bh, LAS unsigned char* lds, const int tidx, const bool nostore) {
;     ...
;         for (int n2 = 0; n2 < 64; n2 += 2) {
;             LOADER_ITER(n2, pfa, pfb);
;             LOADER_ITER(n2 + 1, pfb, pfa);
;         }
.LBB0_367:
	s_cmp_gt_u32 s6, 61
	s_cselect_b64 s[4:5], -1, 0
	s_and_b64 vcc, exec, s[4:5]
	v_lshl_add_u64 v[172:173], v[114:115], 0, s[94:95]
	v_lshl_add_u64 v[170:171], v[116:117], 0, s[94:95]
	v_lshl_add_u64 v[168:169], v[118:119], 0, s[94:95]
	v_lshl_add_u64 v[166:167], v[120:121], 0, s[94:95]
	v_lshl_add_u64 v[164:165], v[122:123], 0, s[94:95]
	v_lshl_add_u64 v[160:161], v[124:125], 0, s[94:95]
	v_lshl_add_u64 v[158:159], v[126:127], 0, s[94:95]
	v_lshl_add_u64 v[156:157], v[128:129], 0, s[94:95]
	v_lshl_add_u64 v[154:155], v[130:131], 0, s[94:95]
	v_lshl_add_u64 v[152:153], v[132:133], 0, s[94:95]
	v_lshl_add_u64 v[150:151], v[134:135], 0, s[94:95]
	v_lshl_add_u64 v[148:149], v[136:137], 0, s[94:95]
	v_lshl_add_u64 v[146:147], v[138:139], 0, s[94:95]
	v_lshl_add_u64 v[144:145], v[140:141], 0, s[94:95]
	s_cbranch_vccnz .LBB0_369
	s_and_b64 vcc, exec, s[0:1]
	s_cbranch_vccnz .Lldr_even_A27
	s_waitcnt vmcnt(35)
	ds_write_b128 v174, v[56:59] offset:57344
	s_waitcnt vmcnt(34)
	ds_write_b128 v174, v[60:63] offset:61440
	s_waitcnt vmcnt(33)
	ds_write_b128 v175, v[64:67] offset:8192
	s_waitcnt vmcnt(32)
	ds_write_b128 v175, v[68:71] offset:12288
	s_waitcnt vmcnt(31)
	ds_write_b128 v175, v[72:75] offset:16384
	s_waitcnt vmcnt(30)
	ds_write_b128 v175, v[76:79] offset:20480
	s_waitcnt vmcnt(29)
	ds_write_b128 v175, v[80:83] offset:24576
	s_waitcnt vmcnt(28)
	ds_write_b128 v175, v[84:87] offset:28672
	s_waitcnt vmcnt(27)
	ds_write_b128 v175, v[88:91] offset:32768
	s_waitcnt vmcnt(26)
	ds_write_b128 v175, v[92:95] offset:36864
	s_waitcnt vmcnt(25)
	ds_write_b128 v175, v[96:99] offset:40960
	s_waitcnt vmcnt(24)
	ds_write_b128 v175, v[100:103] offset:45056
	s_waitcnt vmcnt(23)
	ds_write_b128 v175, v[104:107] offset:49152
	s_waitcnt vmcnt(22)
	ds_write_b128 v175, v[108:111] offset:53248
	s_branch .Lldr_even_ld
.Lldr_even_A27:
	s_waitcnt vmcnt(27)
	ds_write_b128 v174, v[56:59] offset:57344
	s_waitcnt vmcnt(26)
	ds_write_b128 v174, v[60:63] offset:61440
	s_waitcnt vmcnt(25)
	ds_write_b128 v175, v[64:67] offset:8192
	s_waitcnt vmcnt(24)
	ds_write_b128 v175, v[68:71] offset:12288
	s_waitcnt vmcnt(23)
	ds_write_b128 v175, v[72:75] offset:16384
	s_waitcnt vmcnt(22)
	ds_write_b128 v175, v[76:79] offset:20480
	s_waitcnt vmcnt(21)
	ds_write_b128 v175, v[80:83] offset:24576
	s_waitcnt vmcnt(20)
	ds_write_b128 v175, v[84:87] offset:28672
	s_waitcnt vmcnt(19)
	ds_write_b128 v175, v[88:91] offset:32768
	s_waitcnt vmcnt(18)
	ds_write_b128 v175, v[92:95] offset:36864
	s_waitcnt vmcnt(17)
	ds_write_b128 v175, v[96:99] offset:40960
	s_waitcnt vmcnt(16)
	ds_write_b128 v175, v[100:103] offset:45056
	s_waitcnt vmcnt(15)
	ds_write_b128 v175, v[104:107] offset:49152
	s_waitcnt vmcnt(14)
	ds_write_b128 v175, v[108:111] offset:53248
.Lldr_even_ld:
	s_waitcnt lgkmcnt(0)
	v_add_co_u32_e32 v56, vcc, 0x15546000, v172
	s_nop 1
	v_addc_co_u32_e32 v57, vcc, 0, v173, vcc
	v_add_co_u32_e32 v60, vcc, 0x15546000, v170
	global_load_dwordx4 v[56:59], v[56:57], off
	s_nop 0
	v_addc_co_u32_e32 v61, vcc, 0, v171, vcc
	v_add_co_u32_e32 v64, vcc, 0x15546000, v168
	global_load_dwordx4 v[60:63], v[60:61], off
	s_nop 0
	v_addc_co_u32_e32 v65, vcc, 0, v169, vcc
	v_add_co_u32_e32 v68, vcc, 0x15546000, v166
	global_load_dwordx4 v[64:67], v[64:65], off
	s_nop 0
	v_addc_co_u32_e32 v69, vcc, 0, v167, vcc
	v_add_co_u32_e32 v72, vcc, 0x15546000, v164
	global_load_dwordx4 v[68:71], v[68:69], off
	s_nop 0
	v_addc_co_u32_e32 v73, vcc, 0, v165, vcc
	v_add_co_u32_e32 v76, vcc, 0x15546000, v160
	global_load_dwordx4 v[72:75], v[72:73], off
	s_nop 0
	v_addc_co_u32_e32 v77, vcc, 0, v161, vcc
	v_add_co_u32_e32 v80, vcc, 0x15546000, v158
	global_load_dwordx4 v[76:79], v[76:77], off
	s_nop 0
	v_addc_co_u32_e32 v81, vcc, 0, v159, vcc
	v_add_co_u32_e32 v84, vcc, 0x15546000, v156
	global_load_dwordx4 v[80:83], v[80:81], off
	s_nop 0
	v_addc_co_u32_e32 v85, vcc, 0, v157, vcc
	v_add_co_u32_e32 v88, vcc, 0x15546000, v154
	global_load_dwordx4 v[84:87], v[84:85], off
	s_nop 0
	v_addc_co_u32_e32 v89, vcc, 0, v155, vcc
	v_add_co_u32_e32 v92, vcc, 0x15546000, v152
	global_load_dwordx4 v[88:91], v[88:89], off
	s_nop 0
	v_addc_co_u32_e32 v93, vcc, 0, v153, vcc
	v_add_co_u32_e32 v96, vcc, 0x15546000, v150
	global_load_dwordx4 v[92:95], v[92:93], off
	s_nop 0
	v_addc_co_u32_e32 v97, vcc, 0, v151, vcc
	v_add_co_u32_e32 v100, vcc, 0x15546000, v148
	global_load_dwordx4 v[96:99], v[96:97], off
	s_nop 0
	v_addc_co_u32_e32 v101, vcc, 0, v149, vcc
	v_add_co_u32_e32 v104, vcc, 0x15546000, v146
	global_load_dwordx4 v[100:103], v[100:101], off
	s_nop 0
	v_addc_co_u32_e32 v105, vcc, 0, v147, vcc
	v_add_co_u32_e32 v108, vcc, 0x15546000, v144
	global_load_dwordx4 v[104:107], v[104:105], off
	s_nop 0
	v_addc_co_u32_e32 v109, vcc, 0, v145, vcc
	global_load_dwordx4 v[108:111], v[108:109], off
	s_branch .Lldr_even_wr_done

; DI void gdn_scan(const Args& a, int l, int bh, LAS unsigned char* lds, const int tidx, const bool nostore) {
;     ...
;         for (int n2 = 0; n2 < 64; n2 += 2) {
;             LOADER_ITER(n2, pfa, pfb);
;             LOADER_ITER(n2 + 1, pfb, pfa);
;         }
.Lldr_even_st_done:
	s_waitcnt lgkmcnt(0)
	s_barrier
	s_cmp_gt_u32 s6, 60
	s_cbranch_scc1 .Lldr_odd_wr_done
	s_and_b64 vcc, exec, s[0:1]
	s_cbranch_vccnz .Lldr_odd_A27
	s_waitcnt vmcnt(35)
	ds_write_b128 v174, v[0:3]
	s_waitcnt vmcnt(34)
	ds_write_b128 v174, v[4:7] offset:4096
	s_waitcnt vmcnt(33)
	ds_write_b128 v174, v[8:11] offset:8192
	s_waitcnt vmcnt(32)
	ds_write_b128 v174, v[12:15] offset:12288
	s_waitcnt vmcnt(31)
	ds_write_b128 v174, v[16:19] offset:16384
	s_waitcnt vmcnt(30)
	ds_write_b128 v174, v[20:23] offset:20480
	s_waitcnt vmcnt(29)
	ds_write_b128 v174, v[24:27] offset:24576
	s_waitcnt vmcnt(28)
	ds_write_b128 v174, v[28:31] offset:28672
	s_waitcnt vmcnt(27)
	ds_write_b128 v174, v[32:35] offset:32768
	s_waitcnt vmcnt(26)
	ds_write_b128 v174, v[36:39] offset:36864
	s_waitcnt vmcnt(25)
	ds_write_b128 v174, v[40:43] offset:40960
	s_waitcnt vmcnt(24)
	ds_write_b128 v174, v[44:47] offset:45056
	s_waitcnt vmcnt(23)
	ds_write_b128 v174, v[48:51] offset:49152
	s_waitcnt vmcnt(22)
	ds_write_b128 v174, v[52:55] offset:53248
	s_branch .Lldr_odd_ld

; DI void gdn_scan(const Args& a, int l, int bh, LAS unsigned char* lds, const int tidx, const bool nostore) {
;     ...
;         for (int n2 = 0; n2 < 64; n2 += 2) {
;             LOADER_ITER(n2, pfa, pfb);
;             LOADER_ITER(n2 + 1, pfb, pfa);
;         }
.Lldr_odd_ld:
	s_cmp_gt_u32 s6, 58
	s_cbranch_scc1 .Lldr_odd_wr_done
	s_waitcnt lgkmcnt(0)
	v_add_co_u32_e32 v0, vcc, 0x15554000, v172
	s_nop 1
	v_addc_co_u32_e32 v1, vcc, 0, v173, vcc
	v_add_co_u32_e32 v4, vcc, 0x15554000, v170
	global_load_dwordx4 v[0:3], v[0:1], off
	s_nop 0
	v_addc_co_u32_e32 v5, vcc, 0, v171, vcc
	v_add_co_u32_e32 v8, vcc, 0x15554000, v168
	global_load_dwordx4 v[4:7], v[4:5], off
	s_nop 0
	v_addc_co_u32_e32 v9, vcc, 0, v169, vcc
	v_add_co_u32_e32 v12, vcc, 0x15554000, v166
	global_load_dwordx4 v[8:11], v[8:9], off
	s_nop 0
	v_addc_co_u32_e32 v13, vcc, 0, v167, vcc
	v_add_co_u32_e32 v16, vcc, 0x15554000, v164
	global_load_dwordx4 v[12:15], v[12:13], off
	s_nop 0
	v_addc_co_u32_e32 v17, vcc, 0, v165, vcc
	v_add_co_u32_e32 v20, vcc, 0x15554000, v160
	global_load_dwordx4 v[16:19], v[16:17], off
	s_nop 0
	v_addc_co_u32_e32 v21, vcc, 0, v161, vcc
	v_add_co_u32_e32 v24, vcc, 0x15554000, v158
	global_load_dwordx4 v[20:23], v[20:21], off
	s_nop 0
	v_addc_co_u32_e32 v25, vcc, 0, v159, vcc
	v_add_co_u32_e32 v28, vcc, 0x15554000, v156
	global_load_dwordx4 v[24:27], v[24:25], off
	s_nop 0
	v_addc_co_u32_e32 v29, vcc, 0, v157, vcc
	v_add_co_u32_e32 v32, vcc, 0x15554000, v154
	global_load_dwordx4 v[28:31], v[28:29], off
	s_nop 0
	v_addc_co_u32_e32 v33, vcc, 0, v155, vcc
	v_add_co_u32_e32 v36, vcc, 0x15554000, v152
	global_load_dwordx4 v[32:35], v[32:33], off
	s_nop 0
	v_addc_co_u32_e32 v37, vcc, 0, v153, vcc
	v_add_co_u32_e32 v40, vcc, 0x15554000, v150
	global_load_dwordx4 v[36:39], v[36:37], off
	s_nop 0
	v_addc_co_u32_e32 v41, vcc, 0, v151, vcc
	v_add_co_u32_e32 v44, vcc, 0x15554000, v148
	global_load_dwordx4 v[40:43], v[40:41], off
	s_nop 0
	v_addc_co_u32_e32 v45, vcc, 0, v149, vcc
	v_add_co_u32_e32 v48, vcc, 0x15554000, v146
	global_load_dwordx4 v[44:47], v[44:45], off
	s_nop 0
	v_addc_co_u32_e32 v49, vcc, 0, v147, vcc
	v_add_co_u32_e32 v52, vcc, 0x15554000, v144
	global_load_dwordx4 v[48:51], v[48:49], off
	s_nop 0
	v_addc_co_u32_e32 v53, vcc, 0, v145, vcc
	global_load_dwordx4 v[52:55], v[52:53], off
